# P9 192-row tiles on 256 WGs plus dead row groups skip their LN2 statistics and normalisation blocks
# baseline (speedup 1.0000x reference)
.LBB0_660:
	s_or_b64 exec, exec, s[0:1]
.LBB0_662:
	s_or_b64 exec, exec, s[0:1]
	v_mov_b32_e32 v168, v63
	s_waitcnt lgkmcnt(0)
	v_mov_b32_e32 v169, v64
	v_mov_b32_e32 v170, v62
	v_mov_b32_e32 v171, v65
	v_pk_add_f32 v[168:169], v[168:169], v[170:171]
	v_mov_b32_e32 v170, v59
	v_mov_b32_e32 v171, v60
	v_mov_b32_e32 v174, v58
	v_mov_b32_e32 v175, v61
	v_pk_add_f32 v[170:171], v[170:171], v[174:175]
	v_add_f32_e32 v165, v168, v169
	v_pk_add_f32 v[170:171], v[170:171], v[170:171] op_sel_hi:[0,1]
	v_add_f32_e32 v169, 0, v165
	v_add_f32_e32 v175, v54, v55
	v_add_f32_e32 v177, v56, v57
	v_mov_b32_e32 v174, v46
	v_mov_b32_e32 v176, v47
	v_mov_b32_e32 v170, v48
	v_mov_b32_e32 v168, v49
	v_pk_add_f32 v[174:175], v[174:175], v[176:177]
	v_pk_add_f32 v[168:169], v[170:171], v[168:169]
	s_nop 0
	v_pk_add_f32 v[168:169], v[174:175], v[168:169]
	s_nop 0
	v_add_f32_e32 v165, v168, v169
	ds_bpermute_b32 v168, v162, v165
	s_waitcnt lgkmcnt(0)
	v_add_f32_e32 v165, v165, v168
	ds_bpermute_b32 v168, v164, v165
	s_waitcnt lgkmcnt(0)
	v_add_f32_e32 v165, v165, v168
	v_fmamk_f32 v169, v165, 0xbc800000, v65
	v_fmamk_f32 v171, v165, 0xbc800000, v63
	v_fmamk_f32 v168, v165, 0xbc800000, v64
	v_fmamk_f32 v170, v165, 0xbc800000, v62
	v_mul_f32_e32 v171, v171, v171
	v_mul_f32_e32 v169, v169, v169
	v_fmac_f32_e32 v171, v170, v170
	v_fmac_f32_e32 v169, v168, v168
	v_fmamk_f32 v170, v165, 0xbc800000, v61
	v_fmamk_f32 v173, v165, 0xbc800000, v59
	v_add_f32_e32 v168, v171, v169
	v_fmamk_f32 v169, v165, 0xbc800000, v60
	v_fmamk_f32 v171, v165, 0xbc800000, v58
	v_mul_f32_e32 v173, v173, v173
	v_mul_f32_e32 v170, v170, v170
	v_fmac_f32_e32 v173, v171, v171
	v_fmac_f32_e32 v170, v169, v169
	v_add_f32_e32 v169, v173, v170
	v_fmamk_f32 v170, v165, 0xbc800000, v57
	v_fmamk_f32 v173, v165, 0xbc800000, v55
	v_add_f32_e32 v168, v168, v169
	v_fmamk_f32 v169, v165, 0xbc800000, v56
	v_fmamk_f32 v171, v165, 0xbc800000, v54
	v_mul_f32_e32 v173, v173, v173
	v_mul_f32_e32 v170, v170, v170
	v_fmac_f32_e32 v173, v171, v171
	v_fmac_f32_e32 v170, v169, v169
	v_add_f32_e32 v169, v173, v170
	v_fmamk_f32 v170, v165, 0xbc800000, v49
	v_fmamk_f32 v173, v165, 0xbc800000, v47
	v_add_f32_e32 v168, v169, v168
	v_fmamk_f32 v169, v165, 0xbc800000, v48
	v_fmamk_f32 v171, v165, 0xbc800000, v46
	v_mul_f32_e32 v173, v173, v173
	v_mul_f32_e32 v170, v170, v170
	v_fmac_f32_e32 v173, v171, v171
	v_fmac_f32_e32 v170, v169, v169
	v_add_f32_e32 v169, v173, v170
	v_add_f32_e32 v168, v169, v168
	ds_bpermute_b32 v169, v162, v168
	s_waitcnt lgkmcnt(0)
	v_add_f32_e32 v168, v168, v169
	ds_bpermute_b32 v169, v164, v168
	s_and_saveexec_b64 s[0:1], vcc
	s_cbranch_execz .LBB0_664
	s_lshl_b32 s4, s11, 11
	s_add_i32 s4, s2, s4
	v_mul_f32_e32 v170, 0x3c800000, v165
	v_lshl_add_u32 v165, v1, 5, s4
	s_waitcnt lgkmcnt(0)
	v_add_f32_e32 v171, v168, v169
	ds_write_b64 v165, v[170:171] offset:4096

.LBB0_668:
	s_or_b64 exec, exec, s[0:1]
.LBB0_670:
	s_or_b64 exec, exec, s[0:1]
	v_and_b32_e32 v0, 31, v0
	s_waitcnt lgkmcnt(0)
	s_barrier
	s_waitcnt lgkmcnt(0)
	v_lshl_or_b32 v164, s3, 5, v0
	s_add_u32 s8, s54, 0xf580000
	v_add_u32_e32 v0, s18, v164
	s_addc_u32 s9, s55, 0
	v_cmp_gt_u32_e64 s[0:1], 32, v163
	v_ashrrev_i32_e32 v1, 31, v0
	s_and_saveexec_b64 s[2:3], s[0:1]
	s_cbranch_execz .LBB0_672
	v_lshl_add_u32 v162, v164, 5, 0
	ds_read_b128 v[168:171], v162
	ds_read_b128 v[174:177], v162 offset:16
	s_ashr_i32 s11, s10, 31
	s_waitcnt lgkmcnt(1)
	v_add_f32_e32 v162, v168, v170
	s_waitcnt lgkmcnt(0)
	v_add_f32_e32 v162, v162, v174
	v_add_f32_e32 v162, v162, v176
	v_fmamk_f32 v165, v162, 0xbe800000, v168
	v_fmac_f32_e32 v170, 0xbe800000, v162
	v_fmamk_f32 v168, v162, 0xbe800000, v174
	v_fmac_f32_e32 v176, 0xbe800000, v162
	v_mul_f32_e32 v181, v165, v165
	v_mul_f32_e32 v183, v170, v170
	v_mul_f32_e32 v185, v168, v168
	v_mul_f32_e32 v187, v176, v176
	v_mov_b32_e32 v180, v169
	v_mov_b32_e32 v182, v171
	v_mov_b32_e32 v184, v175
	v_mov_b32_e32 v186, v177
	v_pk_add_f32 v[168:169], v[180:181], v[182:183]
	v_pk_add_f32 v[170:171], v[184:185], v[186:187]
	v_mul_f32_e32 v178, 0x3e800000, v162
	v_pk_add_f32 v[168:169], v[168:169], v[170:171]
	s_nop 0
	v_fmamk_f32 v179, v169, 0x42800000, v168
	v_lshlrev_b64 v[168:169], 5, v[0:1]
	v_lshl_add_u64 v[168:169], s[8:9], 0, v[168:169]
	v_lshl_add_u64 v[168:169], s[10:11], 3, v[168:169]
	global_store_dwordx2 v[168:169], v[178:179], off sc1

.LBB0_694:
	s_or_b64 exec, exec, s[2:3]
	s_waitcnt lgkmcnt(0)
	s_barrier
	v_lshl_add_u32 v162, v172, 3, 0
	ds_read_b64 v[164:165], v162 offset:8192
	v_add_u32_e32 v0, s99, v172
	v_ashrrev_i32_e32 v1, 31, v0
	v_lshlrev_b64 v[168:169], 12, v[0:1]
	v_lshl_add_u64 v[168:169], s[52:53], 0, v[168:169]
	s_waitcnt lgkmcnt(0)
	v_sub_f32_e32 v125, v125, v164
	v_sub_f32_e32 v124, v124, v164
	v_sub_f32_e32 v123, v123, v164
	v_sub_f32_e32 v122, v122, v164
	v_sub_f32_e32 v117, v117, v164
	v_sub_f32_e32 v116, v116, v164
	v_sub_f32_e32 v115, v115, v164
	v_sub_f32_e32 v114, v114, v164
	v_sub_f32_e32 v109, v109, v164
	v_sub_f32_e32 v108, v108, v164
	v_sub_f32_e32 v107, v107, v164
	v_sub_f32_e32 v106, v106, v164
	v_sub_f32_e32 v101, v101, v164
	v_sub_f32_e32 v100, v100, v164
	v_sub_f32_e32 v99, v99, v164
	v_sub_f32_e32 v98, v98, v164
	v_pk_mul_f32 v[122:123], v[164:165], v[122:123] op_sel:[1,0]
	v_pk_mul_f32 v[124:125], v[164:165], v[124:125] op_sel:[1,0]
	v_pk_mul_f32 v[114:115], v[164:165], v[114:115] op_sel:[1,0]
	v_pk_mul_f32 v[116:117], v[164:165], v[116:117] op_sel:[1,0]
	v_pk_mul_f32 v[106:107], v[164:165], v[106:107] op_sel:[1,0]
	v_pk_mul_f32 v[108:109], v[164:165], v[108:109] op_sel:[1,0]
	v_pk_mul_f32 v[98:99], v[164:165], v[98:99] op_sel:[1,0]
	v_pk_mul_f32 v[100:101], v[164:165], v[100:101] op_sel:[1,0]
	s_waitcnt vmcnt(2)
	v_pk_fma_f32 v[124:125], v[156:157], v[124:125], v[160:161]
	v_pk_fma_f32 v[122:123], v[154:155], v[122:123], v[158:159]
	v_lshl_add_u64 v[168:169], v[168:169], 0, v[166:167]
	v_pk_fma_f32 v[116:117], v[148:149], v[116:117], v[152:153]
	v_pk_fma_f32 v[114:115], v[146:147], v[114:115], v[150:151]
	s_waitcnt vmcnt(0)
	v_pk_fma_f32 v[108:109], v[140:141], v[108:109], v[144:145]
	v_pk_fma_f32 v[106:107], v[138:139], v[106:107], v[142:143]
	v_pk_fma_f32 v[100:101], v[132:133], v[100:101], v[136:137]
	v_pk_fma_f32 v[98:99], v[130:131], v[98:99], v[134:135]
	global_store_dwordx4 v[168:169], v[122:125], off
	global_store_dwordx4 v[168:169], v[114:117], off offset:16
	global_store_dwordx4 v[168:169], v[106:109], off offset:512
	global_store_dwordx4 v[168:169], v[98:101], off offset:528
	ds_read_b64 v[98:99], v162 offset:8320
	s_waitcnt lgkmcnt(0)
	v_sub_f32_e32 v81, v81, v98
	v_add_u32_e32 v100, 16, v0
	v_ashrrev_i32_e32 v101, 31, v100
	v_lshlrev_b64 v[100:101], 12, v[100:101]
	v_sub_f32_e32 v80, v80, v98
	v_sub_f32_e32 v79, v79, v98
	v_sub_f32_e32 v78, v78, v98
	v_sub_f32_e32 v85, v85, v98
	v_sub_f32_e32 v84, v84, v98
	v_sub_f32_e32 v83, v83, v98
	v_sub_f32_e32 v82, v82, v98
	v_lshl_add_u64 v[100:101], s[52:53], 0, v[100:101]
	v_pk_mul_f32 v[78:79], v[98:99], v[78:79] op_sel:[1,0]
	v_pk_mul_f32 v[80:81], v[98:99], v[80:81] op_sel:[1,0]
	v_pk_mul_f32 v[82:83], v[98:99], v[82:83] op_sel:[1,0]
	v_pk_mul_f32 v[84:85], v[98:99], v[84:85] op_sel:[1,0]
	v_lshl_add_u64 v[100:101], v[100:101], 0, v[166:167]
	v_pk_fma_f32 v[80:81], v[148:149], v[80:81], v[152:153]
	v_pk_fma_f32 v[78:79], v[146:147], v[78:79], v[150:151]
	v_pk_fma_f32 v[84:85], v[156:157], v[84:85], v[160:161]
	v_pk_fma_f32 v[82:83], v[154:155], v[82:83], v[158:159]
	global_store_dwordx4 v[100:101], v[78:81], off offset:16
	global_store_dwordx4 v[100:101], v[82:85], off
	s_nop 0
	v_sub_f32_e32 v79, v89, v98
	v_sub_f32_e32 v78, v88, v98
	v_sub_f32_e32 v81, v87, v98
	v_sub_f32_e32 v80, v86, v98
	v_pk_mul_f32 v[82:83], v[98:99], v[80:81] op_sel:[1,0]
	v_pk_mul_f32 v[78:79], v[98:99], v[78:79] op_sel:[1,0]
	s_nop 0
	v_pk_fma_f32 v[80:81], v[140:141], v[78:79], v[144:145]
	v_pk_fma_f32 v[78:79], v[138:139], v[82:83], v[142:143]
	global_store_dwordx4 v[100:101], v[78:81], off offset:512
	s_nop 1
	v_sub_f32_e32 v79, v93, v98
	v_sub_f32_e32 v78, v92, v98
	v_sub_f32_e32 v81, v91, v98
	v_sub_f32_e32 v80, v90, v98
	v_pk_mul_f32 v[82:83], v[98:99], v[80:81] op_sel:[1,0]
	v_pk_mul_f32 v[78:79], v[98:99], v[78:79] op_sel:[1,0]
	s_nop 0
	v_pk_fma_f32 v[80:81], v[132:133], v[78:79], v[136:137]
	v_pk_fma_f32 v[78:79], v[130:131], v[82:83], v[134:135]
	global_store_dwordx4 v[100:101], v[78:81], off offset:528
	ds_read_b64 v[82:83], v162 offset:8448
	s_nop 0
	v_add_u32_e32 v78, 32, v0
	v_ashrrev_i32_e32 v79, 31, v78
	v_lshlrev_b64 v[84:85], 12, v[78:79]
	s_waitcnt lgkmcnt(0)
	v_sub_f32_e32 v79, v129, v82
	v_sub_f32_e32 v78, v128, v82
	v_sub_f32_e32 v81, v127, v82
	v_sub_f32_e32 v80, v126, v82
	v_pk_mul_f32 v[86:87], v[82:83], v[80:81] op_sel:[1,0]
	v_pk_mul_f32 v[78:79], v[82:83], v[78:79] op_sel:[1,0]
	v_lshl_add_u64 v[84:85], s[52:53], 0, v[84:85]
	v_pk_fma_f32 v[80:81], v[156:157], v[78:79], v[160:161]
	v_pk_fma_f32 v[78:79], v[154:155], v[86:87], v[158:159]
	v_lshl_add_u64 v[84:85], v[84:85], 0, v[166:167]
	global_store_dwordx4 v[84:85], v[78:81], off
	s_nop 1
	v_sub_f32_e32 v79, v121, v82
	v_sub_f32_e32 v78, v120, v82
	v_sub_f32_e32 v81, v119, v82
	v_sub_f32_e32 v80, v118, v82
	v_pk_mul_f32 v[86:87], v[82:83], v[80:81] op_sel:[1,0]
	v_pk_mul_f32 v[78:79], v[82:83], v[78:79] op_sel:[1,0]
	s_nop 0
	v_pk_fma_f32 v[80:81], v[148:149], v[78:79], v[152:153]
	v_pk_fma_f32 v[78:79], v[146:147], v[86:87], v[150:151]
	global_store_dwordx4 v[84:85], v[78:81], off offset:16
	s_nop 1
	v_sub_f32_e32 v79, v113, v82
	v_sub_f32_e32 v78, v112, v82
	v_sub_f32_e32 v81, v111, v82
	v_sub_f32_e32 v80, v110, v82
	v_pk_mul_f32 v[86:87], v[82:83], v[80:81] op_sel:[1,0]
	v_pk_mul_f32 v[78:79], v[82:83], v[78:79] op_sel:[1,0]
	s_nop 0
	v_pk_fma_f32 v[80:81], v[140:141], v[78:79], v[144:145]
	v_pk_fma_f32 v[78:79], v[138:139], v[86:87], v[142:143]
	global_store_dwordx4 v[84:85], v[78:81], off offset:512
	s_nop 1
	v_sub_f32_e32 v79, v97, v82
	v_sub_f32_e32 v78, v96, v82
	v_sub_f32_e32 v81, v95, v82
	v_sub_f32_e32 v80, v94, v82
	v_pk_mul_f32 v[86:87], v[82:83], v[80:81] op_sel:[1,0]
	v_pk_mul_f32 v[78:79], v[82:83], v[78:79] op_sel:[1,0]
	s_nop 0
	v_pk_fma_f32 v[80:81], v[132:133], v[78:79], v[136:137]
	v_pk_fma_f32 v[78:79], v[130:131], v[86:87], v[134:135]
	global_store_dwordx4 v[84:85], v[78:81], off offset:528
	ds_read_b64 v[66:67], v162 offset:9216
	s_waitcnt lgkmcnt(0)
	v_sub_f32_e32 v65, v65, v66
	v_add_u32_e32 v68, 0x60, v0
	v_ashrrev_i32_e32 v69, 31, v68
	v_lshlrev_b64 v[68:69], 12, v[68:69]
	v_sub_f32_e32 v64, v64, v66
	v_sub_f32_e32 v63, v63, v66
	v_sub_f32_e32 v62, v62, v66
	v_sub_f32_e32 v61, v61, v66
	v_sub_f32_e32 v60, v60, v66
	v_sub_f32_e32 v59, v59, v66
	v_sub_f32_e32 v58, v58, v66
	v_sub_f32_e32 v57, v57, v66
	v_sub_f32_e32 v56, v56, v66
	v_sub_f32_e32 v55, v55, v66
	v_sub_f32_e32 v54, v54, v66
	v_sub_f32_e32 v49, v49, v66
	v_sub_f32_e32 v48, v48, v66
	v_sub_f32_e32 v47, v47, v66
	v_sub_f32_e32 v46, v46, v66
	v_pk_mul_f32 v[62:63], v[66:67], v[62:63] op_sel:[1,0]
	v_pk_mul_f32 v[64:65], v[66:67], v[64:65] op_sel:[1,0]
	v_lshl_add_u64 v[68:69], s[52:53], 0, v[68:69]
	v_pk_mul_f32 v[58:59], v[66:67], v[58:59] op_sel:[1,0]
	v_pk_mul_f32 v[60:61], v[66:67], v[60:61] op_sel:[1,0]
	v_pk_mul_f32 v[54:55], v[66:67], v[54:55] op_sel:[1,0]
	v_pk_mul_f32 v[56:57], v[66:67], v[56:57] op_sel:[1,0]
	v_pk_mul_f32 v[46:47], v[66:67], v[46:47] op_sel:[1,0]
	v_pk_mul_f32 v[48:49], v[66:67], v[48:49] op_sel:[1,0]
	v_pk_fma_f32 v[64:65], v[156:157], v[64:65], v[160:161]
	v_pk_fma_f32 v[62:63], v[154:155], v[62:63], v[158:159]
	v_lshl_add_u64 v[68:69], v[68:69], 0, v[166:167]
	v_pk_fma_f32 v[60:61], v[148:149], v[60:61], v[152:153]
	v_pk_fma_f32 v[58:59], v[146:147], v[58:59], v[150:151]
	v_pk_fma_f32 v[56:57], v[140:141], v[56:57], v[144:145]
	v_pk_fma_f32 v[54:55], v[138:139], v[54:55], v[142:143]
	v_pk_fma_f32 v[48:49], v[132:133], v[48:49], v[136:137]
	v_pk_fma_f32 v[46:47], v[130:131], v[46:47], v[134:135]
	global_store_dwordx4 v[68:69], v[62:65], off
	global_store_dwordx4 v[68:69], v[58:61], off offset:16
	global_store_dwordx4 v[68:69], v[54:57], off offset:512
	global_store_dwordx4 v[68:69], v[46:49], off offset:528
	ds_read_b64 v[54:55], v162 offset:9344
	s_waitcnt lgkmcnt(0)
	v_sub_f32_e32 v45, v45, v54
	v_add_u32_e32 v46, 0x70, v0
	v_ashrrev_i32_e32 v47, 31, v46
	v_lshlrev_b64 v[56:57], 12, v[46:47]
	v_sub_f32_e32 v47, v53, v54
	v_sub_f32_e32 v46, v52, v54
	v_sub_f32_e32 v49, v51, v54
	v_sub_f32_e32 v48, v50, v54
	v_pk_mul_f32 v[50:51], v[54:55], v[48:49] op_sel:[1,0]
	v_pk_mul_f32 v[46:47], v[54:55], v[46:47] op_sel:[1,0]
	v_sub_f32_e32 v44, v44, v54
	v_sub_f32_e32 v43, v43, v54
	v_sub_f32_e32 v42, v42, v54
	v_sub_f32_e32 v41, v41, v54
	v_sub_f32_e32 v40, v40, v54
	v_sub_f32_e32 v39, v39, v54
	v_sub_f32_e32 v38, v38, v54
	v_sub_f32_e32 v33, v33, v54
	v_sub_f32_e32 v32, v32, v54
	v_sub_f32_e32 v31, v31, v54
	v_sub_f32_e32 v30, v30, v54
	v_pk_fma_f32 v[48:49], v[156:157], v[46:47], v[160:161]
	v_pk_fma_f32 v[46:47], v[154:155], v[50:51], v[158:159]
	v_lshl_add_u64 v[50:51], s[52:53], 0, v[56:57]
	v_pk_mul_f32 v[42:43], v[54:55], v[42:43] op_sel:[1,0]
	v_pk_mul_f32 v[44:45], v[54:55], v[44:45] op_sel:[1,0]
	v_pk_mul_f32 v[38:39], v[54:55], v[38:39] op_sel:[1,0]
	v_pk_mul_f32 v[40:41], v[54:55], v[40:41] op_sel:[1,0]
	v_pk_mul_f32 v[30:31], v[54:55], v[30:31] op_sel:[1,0]
	v_pk_mul_f32 v[32:33], v[54:55], v[32:33] op_sel:[1,0]
	v_lshl_add_u64 v[50:51], v[50:51], 0, v[166:167]
	v_pk_fma_f32 v[44:45], v[148:149], v[44:45], v[152:153]
	v_pk_fma_f32 v[42:43], v[146:147], v[42:43], v[150:151]
	v_pk_fma_f32 v[40:41], v[140:141], v[40:41], v[144:145]
	v_pk_fma_f32 v[38:39], v[138:139], v[38:39], v[142:143]
	v_pk_fma_f32 v[32:33], v[132:133], v[32:33], v[136:137]
	v_pk_fma_f32 v[30:31], v[130:131], v[30:31], v[134:135]
	global_store_dwordx4 v[50:51], v[46:49], off
	global_store_dwordx4 v[50:51], v[42:45], off offset:16
	global_store_dwordx4 v[50:51], v[38:41], off offset:512
	global_store_dwordx4 v[50:51], v[30:33], off offset:528
	ds_read_b64 v[38:39], v162 offset:9472
	s_waitcnt lgkmcnt(0)
	v_sub_f32_e32 v29, v29, v38
	v_add_u32_e32 v30, 0x80, v0
	v_ashrrev_i32_e32 v31, 31, v30
	v_lshlrev_b64 v[40:41], 12, v[30:31]
	v_sub_f32_e32 v31, v37, v38
	v_sub_f32_e32 v30, v36, v38
	v_sub_f32_e32 v33, v35, v38
	v_sub_f32_e32 v32, v34, v38
	v_pk_mul_f32 v[34:35], v[38:39], v[32:33] op_sel:[1,0]
	v_pk_mul_f32 v[30:31], v[38:39], v[30:31] op_sel:[1,0]
	v_sub_f32_e32 v28, v28, v38
	v_sub_f32_e32 v27, v27, v38
	v_sub_f32_e32 v26, v26, v38
	v_sub_f32_e32 v25, v25, v38
	v_sub_f32_e32 v24, v24, v38
	v_sub_f32_e32 v23, v23, v38
	v_sub_f32_e32 v22, v22, v38
	v_sub_f32_e32 v17, v17, v38
	v_sub_f32_e32 v16, v16, v38
	v_sub_f32_e32 v15, v15, v38
	v_sub_f32_e32 v14, v14, v38
	v_pk_fma_f32 v[32:33], v[156:157], v[30:31], v[160:161]
	v_pk_fma_f32 v[30:31], v[154:155], v[34:35], v[158:159]
	v_lshl_add_u64 v[34:35], s[52:53], 0, v[40:41]
	v_pk_mul_f32 v[26:27], v[38:39], v[26:27] op_sel:[1,0]
	v_pk_mul_f32 v[28:29], v[38:39], v[28:29] op_sel:[1,0]
	v_pk_mul_f32 v[22:23], v[38:39], v[22:23] op_sel:[1,0]
	v_pk_mul_f32 v[24:25], v[38:39], v[24:25] op_sel:[1,0]
	v_pk_mul_f32 v[14:15], v[38:39], v[14:15] op_sel:[1,0]
	v_pk_mul_f32 v[16:17], v[38:39], v[16:17] op_sel:[1,0]
	v_lshl_add_u64 v[34:35], v[34:35], 0, v[166:167]
	v_pk_fma_f32 v[28:29], v[148:149], v[28:29], v[152:153]
	v_pk_fma_f32 v[26:27], v[146:147], v[26:27], v[150:151]
	v_pk_fma_f32 v[24:25], v[140:141], v[24:25], v[144:145]
	v_pk_fma_f32 v[22:23], v[138:139], v[22:23], v[142:143]
	v_pk_fma_f32 v[16:17], v[132:133], v[16:17], v[136:137]
	v_pk_fma_f32 v[14:15], v[130:131], v[14:15], v[134:135]
	global_store_dwordx4 v[34:35], v[30:33], off
	global_store_dwordx4 v[34:35], v[26:29], off offset:16
	global_store_dwordx4 v[34:35], v[22:25], off offset:512
	global_store_dwordx4 v[34:35], v[14:17], off offset:528
